# P3: blocks with blockIdx bit 8 set run the two up-projection GEMM loops before the RWKV prep tiles (the other half keeps prep first)
# speedup vs baseline: 1.0096x; 1.0071x over previous
.LBB0_326:
	s_or_b64 exec, exec, s[0:1]
	s_bitcmp1_b32 s89, 8
	s_cselect_b32 s0, 1, 0
	s_cmp_lg_u32 s26, 0x200
	s_cselect_b32 s0, 0, s0
	v_writelane_b32 v233, s0, 59
.Lp3_redo:
	v_readlane_b32 s0, v234, 63
	v_readlane_b32 s1, v233, 0
	s_xor_b64 s[0:1], s[0:1], -1
	v_writelane_b32 v233, s0, 1
	s_mov_b32 s12, s89
	s_mov_b32 s13, s89
	v_writelane_b32 v233, s1, 2
	v_readlane_b32 s0, v234, 62
	s_lshl_b32 s15, s0, 14
	v_readlane_b32 s0, v235, 7
	v_readlane_b32 s1, v235, 8
	s_andn2_b64 vcc, exec, s[0:1]
	s_waitcnt lgkmcnt(0)
	s_barrier
	v_readlane_b32 s0, v233, 59
	s_nop 3
	s_cmp_eq_u32 s0, 1
	s_cbranch_scc1 .LBB0_327
	s_cmp_eq_u32 s0, 2
	s_cbranch_scc0 .Lp3_norm
	s_cbranch_vccz .LBB0_333
	s_branch .LBB0_329
.Lp3_norm:
	s_cbranch_vccz .LBB0_333

.LBB0_329:
	v_readlane_b32 s0, v233, 59
	s_nop 3
	s_cmp_eq_u32 s0, 1
	s_cbranch_scc0 .Lp3_end
	s_mov_b32 s0, 2
	v_writelane_b32 v233, s0, 59
	s_branch .Lp3_redo

.Lp3_prepdone:
	v_readlane_b32 s0, v233, 59
	s_nop 3
	s_cmp_eq_u32 s0, 2
	s_cbranch_scc1 .LBB0_329
	s_branch .LBB0_327
